# phase 13 (uq/ukv up-projections, store-drain bound): write-through sc1 on the 16 epilogue stores so the lines do not sit dirty in L2
# speedup vs baseline: 1.0021x; 1.0010x over previous
; DEV unsigned cvt_pk_bf16(float lo, float hi) { unsigned r; asm volatile("v_cvt_pk_bf16_f32 %0, %1, %2" : "=v"(r) : "v"(lo), "v"(hi)); return r; }
;     DEV void operator()(const Acc& acc, const Unit& u, int wr, int wc, int fr, int fq, LAS unsigned char*) const {
;     ...
;         int colt = u.pn * 256; bf16_t* base = O0; if (split && colt >= split) { base = O1; colt -= split; }
;         const int row0 = rowbase + u.pz * zrows + u.pm * 256 + wr * 64 + fr, col0 = colt + wc * 32 + 8 * fq;
; #pragma unroll
;         for (int ai = 0; ai < 2; ++ai)
; #pragma unroll
;             for (int m = 0; m < 4; ++m) { const int row = row0 + ai * 128 + m * 16; bf16_t* rowp = base + (size_t)row * ldc + col0;
;                 const float sc = rs ? scale / sqrtf(rs[(size_t)row * 2 + rsi] * rsdiv + EPS) : scale;
; #pragma unroll
;                 for (int bj = 0; bj < 2; ++bj) { const f32x4 v0 = acc[ai][bj][m][0] * sc, v1 = acc[ai][bj][m][1] * sc; u32x4 w;
;                     w.x = cvt_pk_bf16(v0[0], v0[1]); w.y = cvt_pk_bf16(v0[2], v0[3]); w.z = cvt_pk_bf16(v1[0], v1[1]); w.w = cvt_pk_bf16(v1[2], v1[3]);
;                     *(u32x4*)(rowp + bj * 128) = w; } }
.LBB0_2058:
	s_lshl_b32 s25, s38, 8
	s_cmp_lt_i32 s25, s73
	v_readlane_b32 s40, v249, 24
	s_cselect_b64 s[6:7], -1, 0
	v_readlane_b32 s41, v249, 25
	s_or_b64 s[6:7], s[40:41], s[6:7]
	s_and_b64 s[6:7], s[6:7], exec
	s_cselect_b32 s6, s75, s69
	s_cselect_b32 s7, s74, s68
	v_mov_b32_e32 v150, s7
	v_mov_b32_e32 v151, s6
	s_cselect_b32 s6, 0, s73
	s_or_b32 s7, s25, s49
	s_sub_i32 s6, s7, s6
	v_lshl_add_u32 v142, v142, 3, s6
	v_ashrrev_i32_e32 v143, 31, v142
	v_lshl_add_u64 v[142:143], v[142:143], 1, v[150:151]
	v_mul_lo_u32 v152, s59, v140
	v_mul_lo_u32 v141, s58, v141
	v_mad_u64_u32 v[150:151], s[6:7], s58, v140, 0
	v_add3_u32 v151, v151, v141, v152
	v_lshl_add_u64 v[150:151], v[150:151], 1, v[142:143]
	v_pk_mul_f32 v[128:129], v[128:129], v[146:147] op_sel_hi:[1,0]
	v_pk_mul_f32 v[126:127], v[126:127], v[146:147] op_sel_hi:[1,0]
	v_pk_mul_f32 v[152:153], v[124:125], v[146:147] op_sel_hi:[1,0]
	v_pk_mul_f32 v[124:125], v[122:123], v[146:147] op_sel_hi:[1,0]
	v_cvt_pk_bf16_f32 v122, v126, v127
	v_cvt_pk_bf16_f32 v123, v128, v129
	v_pk_mul_f32 v[118:119], v[118:119], v[146:147] op_sel_hi:[1,0]
	v_cvt_pk_bf16_f32 v124, v124, v125
	v_cvt_pk_bf16_f32 v125, v152, v153
	global_store_dwordx4 v[150:151], v[122:125], off sc1
	v_pk_mul_f32 v[120:121], v[120:121], v[146:147] op_sel_hi:[1,0]
	s_and_b64 vcc, exec, s[4:5]
	v_pk_mul_f32 v[122:123], v[116:117], v[146:147] op_sel_hi:[1,0]
	v_pk_mul_f32 v[116:117], v[114:115], v[146:147] op_sel_hi:[1,0]
	v_cvt_pk_bf16_f32 v114, v118, v119
	v_cvt_pk_bf16_f32 v115, v120, v121
	s_nop 0
	v_cvt_pk_bf16_f32 v116, v116, v117
	v_cvt_pk_bf16_f32 v117, v122, v123
	global_store_dwordx4 v[150:151], v[114:117], off offset:256 sc1
	s_nop 1
	v_add_u32_e32 v114, 16, v140
	v_ashrrev_i32_e32 v115, 31, v114
	s_cbranch_vccnz .LBB0_2060
	v_lshl_add_u64 v[116:117], v[114:115], 3, s[20:21]
	v_mov_b32_e32 v116, v190
	v_fma_f32 v116, s27, v116, v180
	v_mul_f32_e32 v117, 0x4f800000, v116
	v_cmp_gt_f32_e32 vcc, s78, v116
	s_nop 1
	v_cndmask_b32_e32 v116, v116, v117, vcc
	v_sqrt_f32_e32 v117, v116
	s_nop 0
	v_add_u32_e32 v118, -1, v117
	v_add_u32_e32 v119, 1, v117
	v_fma_f32 v120, -v118, v117, v116
	v_fma_f32 v121, -v119, v117, v116
	v_cmp_ge_f32_e64 s[6:7], 0, v120
	s_nop 1
	v_cndmask_b32_e64 v117, v117, v118, s[6:7]
	v_cmp_lt_f32_e64 s[6:7], 0, v121
	s_nop 1
	v_cndmask_b32_e64 v117, v117, v119, s[6:7]
	v_mul_f32_e32 v118, 0x37800000, v117
	v_cndmask_b32_e32 v117, v117, v118, vcc
	v_cmp_class_f32_e32 vcc, v116, v181
	s_nop 1
	v_cndmask_b32_e32 v116, v117, v116, vcc
	v_div_scale_f32 v117, s[6:7], v116, v116, 1.0
	v_rcp_f32_e32 v118, v117
	v_div_scale_f32 v119, vcc, 1.0, v116, 1.0
	v_fma_f32 v120, -v117, v118, 1.0
	v_fmac_f32_e32 v118, v120, v118
	v_mul_f32_e32 v120, v119, v118
	v_fma_f32 v121, -v117, v120, v119
	v_fmac_f32_e32 v120, v121, v118
	v_fma_f32 v117, -v117, v120, v119
	v_div_fmas_f32 v117, v117, v118, v120
	v_div_fixup_f32 v144, v117, v116, 1.0
.LBB0_2060:
	v_mul_lo_u32 v116, s59, v114
	v_mul_lo_u32 v117, s58, v115
	v_mad_u64_u32 v[114:115], s[6:7], s58, v114, 0
	v_add3_u32 v115, v115, v117, v116
	v_lshl_add_u64 v[114:115], v[114:115], 1, v[142:143]
	v_pk_mul_f32 v[112:113], v[112:113], v[144:145] op_sel_hi:[1,0]
	v_pk_mul_f32 v[110:111], v[110:111], v[144:145] op_sel_hi:[1,0]
	v_pk_mul_f32 v[116:117], v[108:109], v[144:145] op_sel_hi:[1,0]
	v_pk_mul_f32 v[108:109], v[106:107], v[144:145] op_sel_hi:[1,0]
	v_cvt_pk_bf16_f32 v106, v110, v111
	v_cvt_pk_bf16_f32 v107, v112, v113
	v_pk_mul_f32 v[104:105], v[104:105], v[144:145] op_sel_hi:[1,0]
	v_cvt_pk_bf16_f32 v108, v108, v109
	v_cvt_pk_bf16_f32 v109, v116, v117
	global_store_dwordx4 v[114:115], v[106:109], off sc1
	v_pk_mul_f32 v[102:103], v[102:103], v[144:145] op_sel_hi:[1,0]
	s_and_b64 vcc, exec, s[4:5]
	v_pk_mul_f32 v[106:107], v[100:101], v[144:145] op_sel_hi:[1,0]
	v_pk_mul_f32 v[100:101], v[98:99], v[144:145] op_sel_hi:[1,0]
	v_cvt_pk_bf16_f32 v98, v102, v103
	v_cvt_pk_bf16_f32 v99, v104, v105
	v_mov_b32_e32 v102, 1.0
	v_cvt_pk_bf16_f32 v100, v100, v101
	v_cvt_pk_bf16_f32 v101, v106, v107
	global_store_dwordx4 v[114:115], v[98:101], off offset:256 sc1
	s_nop 1
	v_add_u32_e32 v100, 32, v140
	v_ashrrev_i32_e32 v101, 31, v100
	v_mov_b32_e32 v98, 1.0
	s_cbranch_vccnz .LBB0_2062
	v_lshl_add_u64 v[102:103], v[100:101], 3, s[20:21]
	v_mov_b32_e32 v99, v191
	v_fma_f32 v99, s27, v99, v180
	v_mul_f32_e32 v102, 0x4f800000, v99
	v_cmp_gt_f32_e32 vcc, s78, v99
	s_nop 1
	v_cndmask_b32_e32 v99, v99, v102, vcc
	v_sqrt_f32_e32 v102, v99
	s_nop 0
	v_add_u32_e32 v103, -1, v102
	v_add_u32_e32 v104, 1, v102
	v_fma_f32 v105, -v103, v102, v99
	v_fma_f32 v106, -v104, v102, v99
	v_cmp_ge_f32_e64 s[6:7], 0, v105
	s_nop 1
	v_cndmask_b32_e64 v102, v102, v103, s[6:7]
	v_cmp_lt_f32_e64 s[6:7], 0, v106
	s_nop 1
	v_cndmask_b32_e64 v102, v102, v104, s[6:7]
	v_mul_f32_e32 v103, 0x37800000, v102
	v_cndmask_b32_e32 v102, v102, v103, vcc
	v_cmp_class_f32_e32 vcc, v99, v181
	s_nop 1
	v_cndmask_b32_e32 v99, v102, v99, vcc
	v_div_scale_f32 v102, s[6:7], v99, v99, 1.0
	v_rcp_f32_e32 v103, v102
	v_div_scale_f32 v104, vcc, 1.0, v99, 1.0
	v_fma_f32 v105, -v102, v103, 1.0
	v_fmac_f32_e32 v103, v105, v103
	v_mul_f32_e32 v105, v104, v103
	v_fma_f32 v106, -v102, v105, v104
	v_fmac_f32_e32 v105, v106, v103
	v_fma_f32 v102, -v102, v105, v104
	v_div_fmas_f32 v102, v102, v103, v105
	v_div_fixup_f32 v102, v102, v99, 1.0
; DEV unsigned cvt_pk_bf16(float lo, float hi) { unsigned r; asm volatile("v_cvt_pk_bf16_f32 %0, %1, %2" : "=v"(r) : "v"(lo), "v"(hi)); return r; }
;     DEV void operator()(const Acc& acc, const Unit& u, int wr, int wc, int fr, int fq, LAS unsigned char*) const {
;     ...
;         int colt = u.pn * 256; bf16_t* base = O0; if (split && colt >= split) { base = O1; colt -= split; }
;         const int row0 = rowbase + u.pz * zrows + u.pm * 256 + wr * 64 + fr, col0 = colt + wc * 32 + 8 * fq;
; #pragma unroll
;         for (int ai = 0; ai < 2; ++ai)
; #pragma unroll
;             for (int m = 0; m < 4; ++m) { const int row = row0 + ai * 128 + m * 16; bf16_t* rowp = base + (size_t)row * ldc + col0;
;                 const float sc = rs ? scale / sqrtf(rs[(size_t)row * 2 + rsi] * rsdiv + EPS) : scale;
; #pragma unroll
;                 for (int bj = 0; bj < 2; ++bj) { const f32x4 v0 = acc[ai][bj][m][0] * sc, v1 = acc[ai][bj][m][1] * sc; u32x4 w;
;                     w.x = cvt_pk_bf16(v0[0], v0[1]); w.y = cvt_pk_bf16(v0[2], v0[3]); w.z = cvt_pk_bf16(v1[0], v1[1]); w.w = cvt_pk_bf16(v1[2], v1[3]);
;                     *(u32x4*)(rowp + bj * 128) = w; } }
.LBB0_2062:
	v_mul_lo_u32 v99, s59, v100
	v_mul_lo_u32 v103, s58, v101
	v_mad_u64_u32 v[100:101], s[6:7], s58, v100, 0
	v_add3_u32 v101, v101, v103, v99
	v_lshl_add_u64 v[100:101], v[100:101], 1, v[142:143]
	v_pk_mul_f32 v[94:95], v[94:95], v[102:103] op_sel_hi:[1,0]
	v_pk_mul_f32 v[92:93], v[92:93], v[102:103] op_sel_hi:[1,0]
	v_pk_mul_f32 v[104:105], v[90:91], v[102:103] op_sel_hi:[1,0]
	v_pk_mul_f32 v[90:91], v[88:89], v[102:103] op_sel_hi:[1,0]
	v_cvt_pk_bf16_f32 v88, v92, v93
	v_cvt_pk_bf16_f32 v89, v94, v95
	v_pk_mul_f32 v[84:85], v[84:85], v[102:103] op_sel_hi:[1,0]
	v_cvt_pk_bf16_f32 v90, v90, v91
	v_cvt_pk_bf16_f32 v91, v104, v105
	global_store_dwordx4 v[100:101], v[88:91], off sc1
	v_pk_mul_f32 v[86:87], v[86:87], v[102:103] op_sel_hi:[1,0]
	s_and_b64 vcc, exec, s[4:5]
	v_pk_mul_f32 v[88:89], v[82:83], v[102:103] op_sel_hi:[1,0]
	v_pk_mul_f32 v[82:83], v[80:81], v[102:103] op_sel_hi:[1,0]
	v_cvt_pk_bf16_f32 v80, v84, v85
	v_cvt_pk_bf16_f32 v81, v86, v87
	s_nop 0
	v_cvt_pk_bf16_f32 v82, v82, v83
	v_cvt_pk_bf16_f32 v83, v88, v89
	global_store_dwordx4 v[100:101], v[80:83], off offset:256 sc1
	s_nop 1
	v_add_u32_e32 v80, 48, v140
	v_ashrrev_i32_e32 v81, 31, v80
	s_cbranch_vccnz .LBB0_2064
	v_lshl_add_u64 v[82:83], v[80:81], 3, s[20:21]
	v_mov_b32_e32 v82, v192
	v_fma_f32 v82, s27, v82, v180
	v_mul_f32_e32 v83, 0x4f800000, v82
	v_cmp_gt_f32_e32 vcc, s78, v82
	s_nop 1
	v_cndmask_b32_e32 v82, v82, v83, vcc
	v_sqrt_f32_e32 v83, v82
	s_nop 0
	v_add_u32_e32 v84, -1, v83
	v_add_u32_e32 v85, 1, v83
	v_fma_f32 v86, -v84, v83, v82
	v_fma_f32 v87, -v85, v83, v82
	v_cmp_ge_f32_e64 s[6:7], 0, v86
	s_nop 1
	v_cndmask_b32_e64 v83, v83, v84, s[6:7]
	v_cmp_lt_f32_e64 s[6:7], 0, v87
	s_nop 1
	v_cndmask_b32_e64 v83, v83, v85, s[6:7]
	v_mul_f32_e32 v84, 0x37800000, v83
	v_cndmask_b32_e32 v83, v83, v84, vcc
	v_cmp_class_f32_e32 vcc, v82, v181
	s_nop 1
	v_cndmask_b32_e32 v82, v83, v82, vcc
	v_div_scale_f32 v83, s[6:7], v82, v82, 1.0
	v_rcp_f32_e32 v84, v83
	v_div_scale_f32 v85, vcc, 1.0, v82, 1.0
	v_fma_f32 v86, -v83, v84, 1.0
	v_fmac_f32_e32 v84, v86, v84
	v_mul_f32_e32 v86, v85, v84
	v_fma_f32 v87, -v83, v86, v85
	v_fmac_f32_e32 v86, v87, v84
	v_fma_f32 v83, -v83, v86, v85
	v_div_fmas_f32 v83, v83, v84, v86
	v_div_fixup_f32 v98, v83, v82, 1.0
.LBB0_2064:
	v_mul_lo_u32 v82, s59, v80
	v_mul_lo_u32 v83, s58, v81
	v_mad_u64_u32 v[80:81], s[6:7], s58, v80, 0
	v_add3_u32 v81, v81, v83, v82
	v_lshl_add_u64 v[80:81], v[80:81], 1, v[142:143]
	v_pk_mul_f32 v[78:79], v[78:79], v[98:99] op_sel_hi:[1,0]
	v_pk_mul_f32 v[76:77], v[76:77], v[98:99] op_sel_hi:[1,0]
	v_pk_mul_f32 v[82:83], v[74:75], v[98:99] op_sel_hi:[1,0]
	v_pk_mul_f32 v[74:75], v[72:73], v[98:99] op_sel_hi:[1,0]
	v_cvt_pk_bf16_f32 v72, v76, v77
	v_cvt_pk_bf16_f32 v73, v78, v79
	v_pk_mul_f32 v[70:71], v[70:71], v[98:99] op_sel_hi:[1,0]
	v_cvt_pk_bf16_f32 v74, v74, v75
	v_cvt_pk_bf16_f32 v75, v82, v83
	global_store_dwordx4 v[80:81], v[72:75], off sc1
	v_pk_mul_f32 v[68:69], v[68:69], v[98:99] op_sel_hi:[1,0]
	s_and_b64 vcc, exec, s[4:5]
	v_pk_mul_f32 v[72:73], v[66:67], v[98:99] op_sel_hi:[1,0]
	v_pk_mul_f32 v[66:67], v[64:65], v[98:99] op_sel_hi:[1,0]
	v_cvt_pk_bf16_f32 v64, v68, v69
	v_cvt_pk_bf16_f32 v65, v70, v71
	v_mov_b32_e32 v68, 1.0
	v_cvt_pk_bf16_f32 v66, v66, v67
	v_cvt_pk_bf16_f32 v67, v72, v73
	global_store_dwordx4 v[80:81], v[64:67], off offset:256 sc1
	s_nop 1
	v_add_u32_e32 v66, 0x80, v140
	v_ashrrev_i32_e32 v67, 31, v66
	v_mov_b32_e32 v64, 1.0
	s_cbranch_vccnz .LBB0_2066
	v_lshl_add_u64 v[68:69], v[66:67], 3, s[20:21]
	v_mov_b32_e32 v65, v193
	v_fma_f32 v65, s27, v65, v180
	v_mul_f32_e32 v68, 0x4f800000, v65
	v_cmp_gt_f32_e32 vcc, s78, v65
	s_nop 1
	v_cndmask_b32_e32 v65, v65, v68, vcc
	v_sqrt_f32_e32 v68, v65
	s_nop 0
	v_add_u32_e32 v69, -1, v68
	v_add_u32_e32 v70, 1, v68
	v_fma_f32 v71, -v69, v68, v65
	v_fma_f32 v72, -v70, v68, v65
	v_cmp_ge_f32_e64 s[6:7], 0, v71
	s_nop 1
	v_cndmask_b32_e64 v68, v68, v69, s[6:7]
	v_cmp_lt_f32_e64 s[6:7], 0, v72
	s_nop 1
	v_cndmask_b32_e64 v68, v68, v70, s[6:7]
	v_mul_f32_e32 v69, 0x37800000, v68
	v_cndmask_b32_e32 v68, v68, v69, vcc
	v_cmp_class_f32_e32 vcc, v65, v181
	s_nop 1
	v_cndmask_b32_e32 v65, v68, v65, vcc
	v_div_scale_f32 v68, s[6:7], v65, v65, 1.0
	v_rcp_f32_e32 v69, v68
	v_div_scale_f32 v70, vcc, 1.0, v65, 1.0
	v_fma_f32 v71, -v68, v69, 1.0
	v_fmac_f32_e32 v69, v71, v69
	v_mul_f32_e32 v71, v70, v69
	v_fma_f32 v72, -v68, v71, v70
	v_fmac_f32_e32 v71, v72, v69
	v_fma_f32 v68, -v68, v71, v70
	v_div_fmas_f32 v68, v68, v69, v71
	v_div_fixup_f32 v68, v68, v65, 1.0
; DEV unsigned cvt_pk_bf16(float lo, float hi) { unsigned r; asm volatile("v_cvt_pk_bf16_f32 %0, %1, %2" : "=v"(r) : "v"(lo), "v"(hi)); return r; }
;     DEV void operator()(const Acc& acc, const Unit& u, int wr, int wc, int fr, int fq, LAS unsigned char*) const {
;     ...
;         int colt = u.pn * 256; bf16_t* base = O0; if (split && colt >= split) { base = O1; colt -= split; }
;         const int row0 = rowbase + u.pz * zrows + u.pm * 256 + wr * 64 + fr, col0 = colt + wc * 32 + 8 * fq;
; #pragma unroll
;         for (int ai = 0; ai < 2; ++ai)
; #pragma unroll
;             for (int m = 0; m < 4; ++m) { const int row = row0 + ai * 128 + m * 16; bf16_t* rowp = base + (size_t)row * ldc + col0;
;                 const float sc = rs ? scale / sqrtf(rs[(size_t)row * 2 + rsi] * rsdiv + EPS) : scale;
; #pragma unroll
;                 for (int bj = 0; bj < 2; ++bj) { const f32x4 v0 = acc[ai][bj][m][0] * sc, v1 = acc[ai][bj][m][1] * sc; u32x4 w;
;                     w.x = cvt_pk_bf16(v0[0], v0[1]); w.y = cvt_pk_bf16(v0[2], v0[3]); w.z = cvt_pk_bf16(v1[0], v1[1]); w.w = cvt_pk_bf16(v1[2], v1[3]);
;                     *(u32x4*)(rowp + bj * 128) = w; } }
.LBB0_2066:
	v_mul_lo_u32 v65, s59, v66
	v_mul_lo_u32 v69, s58, v67
	v_mad_u64_u32 v[66:67], s[6:7], s58, v66, 0
	v_add3_u32 v67, v67, v69, v65
	v_lshl_add_u64 v[66:67], v[66:67], 1, v[142:143]
	v_pk_mul_f32 v[62:63], v[62:63], v[68:69] op_sel_hi:[1,0]
	v_pk_mul_f32 v[60:61], v[60:61], v[68:69] op_sel_hi:[1,0]
	v_pk_mul_f32 v[70:71], v[58:59], v[68:69] op_sel_hi:[1,0]
	v_pk_mul_f32 v[58:59], v[56:57], v[68:69] op_sel_hi:[1,0]
	v_cvt_pk_bf16_f32 v56, v60, v61
	v_cvt_pk_bf16_f32 v57, v62, v63
	v_pk_mul_f32 v[52:53], v[52:53], v[68:69] op_sel_hi:[1,0]
	v_cvt_pk_bf16_f32 v58, v58, v59
	v_cvt_pk_bf16_f32 v59, v70, v71
	global_store_dwordx4 v[66:67], v[56:59], off sc1
	v_pk_mul_f32 v[54:55], v[54:55], v[68:69] op_sel_hi:[1,0]
	s_and_b64 vcc, exec, s[4:5]
	v_pk_mul_f32 v[56:57], v[50:51], v[68:69] op_sel_hi:[1,0]
	v_pk_mul_f32 v[50:51], v[48:49], v[68:69] op_sel_hi:[1,0]
	v_cvt_pk_bf16_f32 v48, v52, v53
	v_cvt_pk_bf16_f32 v49, v54, v55
	s_nop 0
	v_cvt_pk_bf16_f32 v50, v50, v51
	v_cvt_pk_bf16_f32 v51, v56, v57
	global_store_dwordx4 v[66:67], v[48:51], off offset:256 sc1
	s_nop 1
	v_add_u32_e32 v48, 0x90, v140
	v_ashrrev_i32_e32 v49, 31, v48
	s_cbranch_vccnz .LBB0_2068
	v_lshl_add_u64 v[50:51], v[48:49], 3, s[20:21]
	v_mov_b32_e32 v50, v194
	v_fma_f32 v50, s27, v50, v180
	v_mul_f32_e32 v51, 0x4f800000, v50
	v_cmp_gt_f32_e32 vcc, s78, v50
	s_nop 1
	v_cndmask_b32_e32 v50, v50, v51, vcc
	v_sqrt_f32_e32 v51, v50
	s_nop 0
	v_add_u32_e32 v52, -1, v51
	v_add_u32_e32 v53, 1, v51
	v_fma_f32 v54, -v52, v51, v50
	v_fma_f32 v55, -v53, v51, v50
	v_cmp_ge_f32_e64 s[6:7], 0, v54
	s_nop 1
	v_cndmask_b32_e64 v51, v51, v52, s[6:7]
	v_cmp_lt_f32_e64 s[6:7], 0, v55
	s_nop 1
	v_cndmask_b32_e64 v51, v51, v53, s[6:7]
	v_mul_f32_e32 v52, 0x37800000, v51
	v_cndmask_b32_e32 v51, v51, v52, vcc
	v_cmp_class_f32_e32 vcc, v50, v181
	s_nop 1
	v_cndmask_b32_e32 v50, v51, v50, vcc
	v_div_scale_f32 v51, s[6:7], v50, v50, 1.0
	v_rcp_f32_e32 v52, v51
	v_div_scale_f32 v53, vcc, 1.0, v50, 1.0
	v_fma_f32 v54, -v51, v52, 1.0
	v_fmac_f32_e32 v52, v54, v52
	v_mul_f32_e32 v54, v53, v52
	v_fma_f32 v55, -v51, v54, v53
	v_fmac_f32_e32 v54, v55, v52
	v_fma_f32 v51, -v51, v54, v53
	v_div_fmas_f32 v51, v51, v52, v54
	v_div_fixup_f32 v64, v51, v50, 1.0
.LBB0_2068:
	v_mul_lo_u32 v50, s59, v48
	v_mul_lo_u32 v51, s58, v49
	v_mad_u64_u32 v[48:49], s[6:7], s58, v48, 0
	v_add3_u32 v49, v49, v51, v50
	v_lshl_add_u64 v[48:49], v[48:49], 1, v[142:143]
	v_pk_mul_f32 v[46:47], v[46:47], v[64:65] op_sel_hi:[1,0]
	v_pk_mul_f32 v[44:45], v[44:45], v[64:65] op_sel_hi:[1,0]
	v_pk_mul_f32 v[50:51], v[42:43], v[64:65] op_sel_hi:[1,0]
	v_pk_mul_f32 v[42:43], v[40:41], v[64:65] op_sel_hi:[1,0]
	v_cvt_pk_bf16_f32 v40, v44, v45
	v_cvt_pk_bf16_f32 v41, v46, v47
	v_pk_mul_f32 v[38:39], v[38:39], v[64:65] op_sel_hi:[1,0]
	v_cvt_pk_bf16_f32 v42, v42, v43
	v_cvt_pk_bf16_f32 v43, v50, v51
	global_store_dwordx4 v[48:49], v[40:43], off sc1
	v_pk_mul_f32 v[36:37], v[36:37], v[64:65] op_sel_hi:[1,0]
	s_and_b64 vcc, exec, s[4:5]
	v_pk_mul_f32 v[40:41], v[34:35], v[64:65] op_sel_hi:[1,0]
	v_pk_mul_f32 v[34:35], v[32:33], v[64:65] op_sel_hi:[1,0]
	v_cvt_pk_bf16_f32 v32, v36, v37
	v_cvt_pk_bf16_f32 v33, v38, v39
	v_mov_b32_e32 v36, 1.0
	v_cvt_pk_bf16_f32 v34, v34, v35
	v_cvt_pk_bf16_f32 v35, v40, v41
	global_store_dwordx4 v[48:49], v[32:35], off offset:256 sc1
	s_nop 1
	v_add_u32_e32 v34, 0xa0, v140
	v_ashrrev_i32_e32 v35, 31, v34
	v_mov_b32_e32 v32, 1.0
	s_cbranch_vccnz .LBB0_2070
	v_lshl_add_u64 v[36:37], v[34:35], 3, s[20:21]
	v_mov_b32_e32 v33, v195
	v_fma_f32 v33, s27, v33, v180
	v_mul_f32_e32 v36, 0x4f800000, v33
	v_cmp_gt_f32_e32 vcc, s78, v33
	s_nop 1
	v_cndmask_b32_e32 v33, v33, v36, vcc
	v_sqrt_f32_e32 v36, v33
	s_nop 0
	v_add_u32_e32 v37, -1, v36
	v_add_u32_e32 v38, 1, v36
	v_fma_f32 v39, -v37, v36, v33
	v_fma_f32 v40, -v38, v36, v33
	v_cmp_ge_f32_e64 s[6:7], 0, v39
	s_nop 1
	v_cndmask_b32_e64 v36, v36, v37, s[6:7]
	v_cmp_lt_f32_e64 s[6:7], 0, v40
	s_nop 1
	v_cndmask_b32_e64 v36, v36, v38, s[6:7]
	v_mul_f32_e32 v37, 0x37800000, v36
	v_cndmask_b32_e32 v36, v36, v37, vcc
	v_cmp_class_f32_e32 vcc, v33, v181
	s_nop 1
	v_cndmask_b32_e32 v33, v36, v33, vcc
	v_div_scale_f32 v36, s[6:7], v33, v33, 1.0
	v_rcp_f32_e32 v37, v36
	v_div_scale_f32 v38, vcc, 1.0, v33, 1.0
	v_fma_f32 v39, -v36, v37, 1.0
	v_fmac_f32_e32 v37, v39, v37
	v_mul_f32_e32 v39, v38, v37
	v_fma_f32 v40, -v36, v39, v38
	v_fmac_f32_e32 v39, v40, v37
	v_fma_f32 v36, -v36, v39, v38
	v_div_fmas_f32 v36, v36, v37, v39
	v_div_fixup_f32 v36, v36, v33, 1.0
; DEV unsigned cvt_pk_bf16(float lo, float hi) { unsigned r; asm volatile("v_cvt_pk_bf16_f32 %0, %1, %2" : "=v"(r) : "v"(lo), "v"(hi)); return r; }
;     DEV void operator()(const Acc& acc, const Unit& u, int wr, int wc, int fr, int fq, LAS unsigned char*) const {
;     ...
;         int colt = u.pn * 256; bf16_t* base = O0; if (split && colt >= split) { base = O1; colt -= split; }
;         const int row0 = rowbase + u.pz * zrows + u.pm * 256 + wr * 64 + fr, col0 = colt + wc * 32 + 8 * fq;
; #pragma unroll
;         for (int ai = 0; ai < 2; ++ai)
; #pragma unroll
;             for (int m = 0; m < 4; ++m) { const int row = row0 + ai * 128 + m * 16; bf16_t* rowp = base + (size_t)row * ldc + col0;
;                 const float sc = rs ? scale / sqrtf(rs[(size_t)row * 2 + rsi] * rsdiv + EPS) : scale;
; #pragma unroll
;                 for (int bj = 0; bj < 2; ++bj) { const f32x4 v0 = acc[ai][bj][m][0] * sc, v1 = acc[ai][bj][m][1] * sc; u32x4 w;
;                     w.x = cvt_pk_bf16(v0[0], v0[1]); w.y = cvt_pk_bf16(v0[2], v0[3]); w.z = cvt_pk_bf16(v1[0], v1[1]); w.w = cvt_pk_bf16(v1[2], v1[3]);
;                     *(u32x4*)(rowp + bj * 128) = w; } }
.LBB0_2070:
	v_mul_lo_u32 v33, s59, v34
	v_mul_lo_u32 v37, s58, v35
	v_mad_u64_u32 v[34:35], s[6:7], s58, v34, 0
	v_add3_u32 v35, v35, v37, v33
	v_lshl_add_u64 v[34:35], v[34:35], 1, v[142:143]
	v_pk_mul_f32 v[30:31], v[30:31], v[36:37] op_sel_hi:[1,0]
	v_pk_mul_f32 v[28:29], v[28:29], v[36:37] op_sel_hi:[1,0]
	v_pk_mul_f32 v[38:39], v[26:27], v[36:37] op_sel_hi:[1,0]
	v_pk_mul_f32 v[26:27], v[24:25], v[36:37] op_sel_hi:[1,0]
	v_cvt_pk_bf16_f32 v24, v28, v29
	v_cvt_pk_bf16_f32 v25, v30, v31
	v_pk_mul_f32 v[20:21], v[20:21], v[36:37] op_sel_hi:[1,0]
	v_cvt_pk_bf16_f32 v26, v26, v27
	v_cvt_pk_bf16_f32 v27, v38, v39
	global_store_dwordx4 v[34:35], v[24:27], off sc1
	v_pk_mul_f32 v[22:23], v[22:23], v[36:37] op_sel_hi:[1,0]
	s_and_b64 vcc, exec, s[4:5]
	v_pk_mul_f32 v[24:25], v[18:19], v[36:37] op_sel_hi:[1,0]
	v_pk_mul_f32 v[18:19], v[16:17], v[36:37] op_sel_hi:[1,0]
	v_cvt_pk_bf16_f32 v16, v20, v21
	v_cvt_pk_bf16_f32 v17, v22, v23
	s_nop 0
	v_cvt_pk_bf16_f32 v18, v18, v19
	v_cvt_pk_bf16_f32 v19, v24, v25
	global_store_dwordx4 v[34:35], v[16:19], off offset:256 sc1
	s_nop 1
	v_add_u32_e32 v16, 0xb0, v140
	v_ashrrev_i32_e32 v17, 31, v16
	s_cbranch_vccnz .LBB0_2072
	v_lshl_add_u64 v[18:19], v[16:17], 3, s[20:21]
	v_mov_b32_e32 v18, v196
	v_fma_f32 v18, s27, v18, v180
	v_mul_f32_e32 v19, 0x4f800000, v18
	v_cmp_gt_f32_e32 vcc, s78, v18
	s_nop 1
	v_cndmask_b32_e32 v18, v18, v19, vcc
	v_sqrt_f32_e32 v19, v18
	s_nop 0
	v_add_u32_e32 v20, -1, v19
	v_add_u32_e32 v21, 1, v19
	v_fma_f32 v22, -v20, v19, v18
	v_fma_f32 v23, -v21, v19, v18
	v_cmp_ge_f32_e64 s[4:5], 0, v22
	s_nop 1
	v_cndmask_b32_e64 v19, v19, v20, s[4:5]
	v_cmp_lt_f32_e64 s[4:5], 0, v23
	s_nop 1
	v_cndmask_b32_e64 v19, v19, v21, s[4:5]
	v_mul_f32_e32 v20, 0x37800000, v19
	v_cndmask_b32_e32 v19, v19, v20, vcc
	v_cmp_class_f32_e32 vcc, v18, v181
	s_nop 1
	v_cndmask_b32_e32 v18, v19, v18, vcc
	v_div_scale_f32 v19, s[4:5], v18, v18, 1.0
	v_rcp_f32_e32 v20, v19
	v_div_scale_f32 v21, vcc, 1.0, v18, 1.0
	v_fma_f32 v22, -v19, v20, 1.0
	v_fmac_f32_e32 v20, v22, v20
	v_mul_f32_e32 v22, v21, v20
	v_fma_f32 v23, -v19, v22, v21
	v_fmac_f32_e32 v22, v23, v20
	v_fma_f32 v19, -v19, v22, v21
	v_div_fmas_f32 v19, v19, v20, v22
	v_div_fixup_f32 v32, v19, v18, 1.0
.LBB0_2072:
	v_mul_lo_u32 v18, s59, v16
	v_mul_lo_u32 v19, s58, v17
	v_mad_u64_u32 v[16:17], s[4:5], s58, v16, 0
	v_add3_u32 v17, v17, v19, v18
	v_lshl_add_u64 v[16:17], v[16:17], 1, v[142:143]
	v_pk_mul_f32 v[14:15], v[14:15], v[32:33] op_sel_hi:[1,0]
	v_pk_mul_f32 v[12:13], v[12:13], v[32:33] op_sel_hi:[1,0]
	v_pk_mul_f32 v[18:19], v[10:11], v[32:33] op_sel_hi:[1,0]
	v_pk_mul_f32 v[10:11], v[8:9], v[32:33] op_sel_hi:[1,0]
	v_cvt_pk_bf16_f32 v8, v12, v13
	v_cvt_pk_bf16_f32 v9, v14, v15
	s_and_b64 vcc, exec, s[2:3]
	v_cvt_pk_bf16_f32 v10, v10, v11
	v_cvt_pk_bf16_f32 v11, v18, v19
	global_store_dwordx4 v[16:17], v[8:11], off sc1
	s_mov_b64 s[2:3], -1
	v_pk_mul_f32 v[6:7], v[6:7], v[32:33] op_sel_hi:[1,0]
	v_pk_mul_f32 v[8:9], v[2:3], v[32:33] op_sel_hi:[1,0]
	v_pk_mul_f32 v[2:3], v[0:1], v[32:33] op_sel_hi:[1,0]
	v_pk_mul_f32 v[4:5], v[4:5], v[32:33] op_sel_hi:[1,0]
	s_nop 0
	v_cvt_pk_bf16_f32 v0, v4, v5
	v_cvt_pk_bf16_f32 v1, v6, v7
	v_cvt_pk_bf16_f32 v2, v2, v3
	v_cvt_pk_bf16_f32 v3, v8, v9
	global_store_dwordx4 v[16:17], v[0:3], off offset:256 sc1
	s_cbranch_vccnz .LBB0_2038
	s_andn2_b64 vcc, exec, s[16:17]
	s_cbranch_vccnz .LBB0_2037
	s_barrier
	s_branch .LBB0_2037
